# v98: GEMM main loop: per-cluster priority flips removed, one static s_setprio 1 for waves 4-7 before the tile loop (reset at phase end)
# baseline (speedup 1.0000x reference)
.LBB0_9:
	s_mul_i32 s3, s6, 3
	s_getpc_b64 s[0:1]
	s_add_u32 s0, s0, PROG@rel32@lo+4
	s_addc_u32 s1, s1, PROG@rel32@hi+12
	s_and_b32 s2, s3, -4
	s_add_u32 s0, s0, s2
	s_addc_u32 s1, s1, 0
	s_load_dwordx2 s[0:1], s[0:1], 0x0
	s_and_b32 s3, s3, 3
	s_lshl_b32 s3, s3, 3
	s_waitcnt lgkmcnt(0)
	s_lshr_b64 s[0:1], s[0:1], s3
	s_and_b32 s2, s0, 0xffff
	v_mov_b32_e32 v0, s2
	s_bfe_u32 s2, s0, 0x80010
	v_mov_b32_e32 v2, s2
	s_cmp_gt_u32 s6, 1
	s_cbranch_scc1 .Lsm_done
	v_readlane_b32 s0, v254, 39
	v_readlane_b32 s1, v254, 40
	s_add_u32 s0, s0, 0xc000
	s_addc_u32 s1, s1, 0
	s_cmp_eq_u32 s6, 1
	s_cbranch_scc1 .Lsm_cache
	s_getreg_b32 s2, hwreg(HW_REG_XCC_ID, 0, 4)
	s_and_b32 s2, s2, 15
	s_lshl_b32 s2, 1, s2
	s_and_b32 s3, s66, 7
	s_lshl_b32 s3, s3, 2
	s_add_u32 s0, s0, s3
	s_addc_u32 s1, s1, 0
	v_mov_b32_e32 v3, s2
	s_mov_b64 s[2:3], exec
	s_mov_b64 exec, 1
	global_atomic_or v1, v3, s[0:1]
	s_mov_b64 exec, s[2:3]
	s_branch .Lsm_done
	s_nop 0
.Lsm_cache:
	global_load_dwordx4 v[4:7], v1, s[0:1] sc1
	global_load_dwordx4 v[8:11], v1, s[0:1] offset:16 sc1
	s_waitcnt vmcnt(0)
	v_add_u32_e32 v3, -1, v4
	v_and_b32_e32 v3, v3, v4
	v_add_u32_e32 v4, -1, v5
	v_and_or_b32 v3, v4, v5, v3
	v_add_u32_e32 v4, -1, v6
	v_and_or_b32 v3, v4, v6, v3
	v_add_u32_e32 v4, -1, v7
	v_and_or_b32 v3, v4, v7, v3
	v_add_u32_e32 v4, -1, v8
	v_and_or_b32 v3, v4, v8, v3
	v_add_u32_e32 v4, -1, v9
	v_and_or_b32 v3, v4, v9, v3
	v_add_u32_e32 v4, -1, v10
	v_and_or_b32 v3, v4, v10, v3
	v_add_u32_e32 v4, -1, v11
	v_and_or_b32 v3, v4, v11, v3
	s_nop 0
	v_readfirstlane_b32 s2, v3
	s_nop 1
	v_writelane_b32 v255, s2, 63

.LBB0_384:
	s_add_i32 m0, s57, 0x18000
	v_lshl_add_u64 v[2:3], v[2:3], 0, s[4:5]
	s_waitcnt vmcnt(2)
	s_barrier
	global_load_lds_dwordx4 v[2:3], off
	v_lshl_add_u64 v[2:3], v[4:5], 0, s[4:5]
	s_add_i32 m0, s57, 0x1a000
	s_add_i32 s69, s57, 0x8000
	global_load_lds_dwordx4 v[2:3], off
	v_lshl_add_u64 v[2:3], v[10:11], 0, s[4:5]
	s_mov_b32 m0, s69
	s_add_i32 s84, s57, 0xa000
	global_load_lds_dwordx4 v[2:3], off
	v_lshl_add_u64 v[2:3], v[12:13], 0, s[4:5]
	s_mov_b32 m0, s84
	v_bfe_u32 v236, v0, 4, 2
	global_load_lds_dwordx4 v[2:3], off
	s_add_i32 m0, s57, 0x1c000
	v_lshl_add_u64 v[2:3], v[6:7], 0, s[4:5]
	global_load_lds_dwordx4 v[2:3], off
	v_lshl_add_u64 v[2:3], v[8:9], 0, s[4:5]
	s_add_i32 m0, s57, 0x1e000
	v_and_b32_e32 v235, 15, v0
	global_load_lds_dwordx4 v[2:3], off
	v_lshlrev_b32_e32 v20, 4, v236
	v_lshlrev_b32_e32 v0, 2, v0
	s_and_b32 s40, s10, 3
	s_lshr_b32 s66, s62, 6
	s_lshl_b32 s67, s1, 6
	v_lshl_or_b32 v20, v235, 6, v20
	s_lshl_b32 s1, s1, 13
	v_and_b32_e32 v0, 32, v0
	v_bitop3_b32 v21, v20, s1, v0 bitop3:0xde
	s_lshl_b32 s68, s40, 5
	s_lshl_b32 s1, s40, 12
	s_add_i32 s85, s66, -2
	s_cmpk_lt_u32 s0, 0x100
	s_cselect_b64 s[94:95], -1, 0
	s_lshr_b32 s0, s34, 3
	v_writelane_b32 v255, s0, 47
	s_add_i32 s0, s0, 1
	v_writelane_b32 v255, s0, 43
	s_ashr_i32 s92, s53, 31
	v_readlane_b32 s36, v255, 5
	s_ashr_i32 s93, s52, 31
	s_and_b32 s61, s34, 7
	s_lshl_b64 s[72:73], s[62:63], 9
	s_lshl_b64 s[74:75], s[6:7], 9
	v_readlane_b32 s38, v255, 7
	v_readlane_b32 s39, v255, 8
	s_add_u32 s76, s38, 0xd000000
	s_addc_u32 s77, s39, 0
	s_add_u32 s78, s38, 0xe800000
	s_addc_u32 s79, s39, 0
	s_add_u32 s0, s38, 0x10000000
	v_bitop3_b32 v237, v20, s1, v0 bitop3:0xde
	s_addc_u32 s1, s39, 0
	s_add_u32 s44, s38, 0x11800000
	s_addc_u32 s45, s39, 0
	s_add_u32 s96, s38, 0x13000000
	s_addc_u32 s97, s39, 0
	v_readlane_b32 s37, v255, 6
	s_add_u32 s6, s36, 0x9040400
	s_addc_u32 s7, s37, 0
	v_writelane_b32 v255, s6, 1
	v_cvt_f32_u32_e32 v0, s54
	s_waitcnt vmcnt(6)
	v_cndmask_b32_e64 v178, 1.0, v228, s[22:23]
	v_writelane_b32 v255, s7, 2
	s_add_u32 s6, s36, 0x7040400
	s_addc_u32 s7, s37, 0
	v_writelane_b32 v255, s6, 59
	v_rcp_iflag_f32_e32 v0, v0
	s_mov_b32 s35, s63
	v_writelane_b32 v255, s7, 60
	v_mov_b32_e32 v180, v178
	v_readlane_b32 s36, v255, 53
	v_readlane_b32 s37, v255, 54
	s_cmp_eq_u64 s[36:37], 0
	s_cselect_b64 s[6:7], -1, 0
	v_readlane_b32 s38, v255, 55
	v_readlane_b32 s39, v255, 56
	v_writelane_b32 v255, s6, 61
	v_mul_f32_e32 v0, 0x4f7ffffe, v0
	v_cvt_u32_f32_e32 v0, v0
	v_writelane_b32 v255, s7, 62
	s_mov_b32 s6, s28
	s_mov_b32 s7, s28
	v_writelane_b32 v255, s6, 49
	v_mov_b32_e32 v181, v178
	s_mov_b32 s29, s28
	v_writelane_b32 v255, s7, 50
	s_mov_b32 s43, 0
	v_readlane_b32 s6, v255, 20
	v_readlane_b32 s7, v255, 21
	s_cmp_lg_u64 s[6:7], 0
	s_cselect_b64 s[6:7], -1, 0
	v_writelane_b32 v255, s6, 30
	v_add_u32_e32 v238, 0, v21
	s_mov_b64 s[18:19], s[2:3]
	v_writelane_b32 v255, s7, 31
	v_readfirstlane_b32 s7, v0
	v_cvt_f32_u32_e32 v0, s55
	s_sub_i32 s6, 0, s54
	s_mul_i32 s6, s6, s7
	s_mul_hi_u32 s6, s7, s6
	v_rcp_iflag_f32_e32 v0, v0
	s_add_i32 s62, s7, s6
	s_sub_i32 s6, 0, s55
	v_readlane_b32 s36, v255, 16
	v_mul_f32_e32 v0, 0x4f7ffffe, v0
	v_cvt_u32_f32_e32 v0, v0
	s_mov_b64 s[20:21], s[8:9]
	v_readlane_b32 s37, v255, 17
	v_writelane_b32 v255, s40, 12
	v_readfirstlane_b32 s7, v0
	v_add_u32_e32 v0, v19, v17
	v_add_lshl_u32 v0, v0, v18, 1
	s_mul_i32 s6, s6, s7
	v_lshl_add_u64 v[182:183], s[50:51], 0, v[0:1]
	v_add_u32_e32 v0, v16, v14
	s_mul_hi_u32 s6, s7, s6
	v_add_lshl_u32 v0, v0, v15, 1
	s_add_i32 s30, s7, s6
	v_lshl_add_u64 v[184:185], s[50:51], 0, v[0:1]
	s_barrier
	v_readlane_b32 vcc_lo, v254, 63
	s_cmp_ge_u32 vcc_lo, 4
	s_cbranch_scc0 .Lprio_done
	s_setprio 1
.Lprio_done:
	s_branch .LBB0_387
.LBB0_385:
	s_mov_b64 s[2:3], 0

.LBB0_798:
	s_waitcnt vmcnt(0)
	s_setprio 0
	v_readlane_b32 s76, v254, 39
	v_readlane_b32 s84, v254, 46
	v_readlane_b32 s94, v254, 52
	v_readlane_b32 s56, v254, 54
	v_readlane_b32 s18, v254, 61
	v_readlane_b32 s58, v255, 22
	v_readlane_b32 s60, v255, 14
	v_readlane_b32 s68, v255, 32
	v_readlane_b32 s70, v255, 34
	v_readlane_b32 s66, v254, 38
	v_readlane_b32 s77, v254, 40
	v_readlane_b32 s78, v254, 41
	v_readlane_b32 s92, v254, 43
	s_movk_i32 s93, 0x80
	v_readlane_b32 s96, v254, 44
	v_readlane_b32 s85, v254, 47
	v_readlane_b32 s95, v254, 53
	v_readlane_b32 s57, v254, 55
	v_readlane_b32 s29, v254, 56
	v_readlane_b32 s35, v254, 57
	v_readlane_b32 s38, v254, 58
	s_mov_b32 s39, 0x12000
	s_movk_i32 s40, 0x3000
	s_mov_b32 s41, 0x18000
	s_mov_b32 s42, 0x9000
	s_movk_i32 s43, 0xffe0
	s_mov_b32 s44, 0x28000
	s_mov_b32 s45, 0x7f800000
	s_mov_b64 s[50:51], 0x48000
	v_readlane_b32 s19, v254, 62
	v_readlane_b32 s59, v255, 23
	v_readlane_b32 s61, v255, 15
	v_readlane_b32 s67, v255, 26
	v_readlane_b32 s80, v255, 29
	v_readlane_b32 s69, v255, 33
	v_readlane_b32 s71, v255, 35
	s_barrier
	v_readlane_b32 s0, v255, 0
	s_cmp_lg_u32 s0, 0
	s_cbranch_scc1 .Lfz_nosig
	v_readlane_b32 s0, v255, 11
	s_cmp_eq_u32 s0, 4
	s_cselect_b32 s1, 1, 0
	s_cmp_eq_u32 s0, 8
	s_cselect_b32 s1, 1, s1
	s_cmp_eq_u32 s1, 0
	s_cbranch_scc1 .Lfz_nosig
	s_cmpk_gt_i32 s67, 191
	s_cbranch_scc1 .Lfz_nosig
	v_readlane_b32 s0, v254, 63
	s_cmp_lg_u32 s0, 0
	s_cbranch_scc1 .Lfz_nosig
	s_and_b32 s0, s67, 7
	s_mul_i32 s0, s0, 6
	s_lshr_b32 s1, s67, 3
	s_mul_i32 s2, s1, 43
	s_lshr_b32 s2, s2, 8
	s_mul_i32 s3, s2, 6
	s_sub_i32 s1, s1, s3
	s_add_i32 s0, s0, s1
	s_lshl_b32 s0, s0, 2
	s_lshl_b32 s1, s18, 8
	s_add_i32 s0, s0, s1
	s_add_i32 s0, s0, 0x10000
	v_readlane_b32 s2, v255, 7
	v_readlane_b32 s3, v255, 8
	s_add_u32 s2, s2, s0
	s_addc_u32 s3, s3, 0
	v_readlane_b32 s0, v255, 63
	s_cmp_eq_u32 s0, 0
	s_cbranch_scc1 .Lfz_local
	buffer_wbl2 sc1
	s_waitcnt vmcnt(0)
